# GEMM K-loops: per-lane global offsets computed once per tile, K advance on SGPR base pointers
# speedup vs baseline: 1.0049x; 1.0042x over previous
.LBB0_85:
	v_add3_u32 v238, v232, v233, v236
	v_add3_u32 v239, v234, v233, v237
	v_add3_u32 v236, v232, v235, v236
	v_add3_u32 v237, v234, v235, v237
	v_add_u32_e32 v236, 0x10000, v236
	v_add_u32_e32 v237, 0x10000, v237
	v_add_u32_e32 v254, 0x8000, v229
	v_add_u32_e32 v255, 0x8000, v230
	ds_read_b128 v[164:167], v238
	ds_read_b128 v[168:171], v238 offset:256
	ds_read_b128 v[172:175], v238 offset:512
	ds_read_b128 v[192:195], v238 offset:768
	ds_read_b128 v[176:179], v236
	ds_read_b128 v[180:183], v236 offset:256
	ds_read_b128 v[184:187], v236 offset:512
	ds_read_b128 v[188:191], v236 offset:768
	ds_read_b128 v[196:199], v238 offset:1024
	ds_read_b128 v[200:203], v238 offset:1280
	ds_read_b128 v[204:207], v238 offset:1536
	ds_read_b128 v[208:211], v238 offset:1792
	s_nop 0
	v_xor_b32_e32 v238, 0x8000, v238
	v_xor_b32_e32 v236, 0x8000, v236
	v_add_u32_e32 v246, v227, v228
	v_add_u32_e32 v247, v227, v231
	v_lshlrev_b32_e32 v246, 1, v246
	v_lshlrev_b32_e32 v247, 1, v247
	v_add_u32_e32 v248, 0x80000, v246
	v_add_u32_e32 v249, 0x100000, v246
	v_add_u32_e32 v250, 0x180000, v246
	v_add_u32_e32 v251, 0x80000, v247
	v_add_u32_e32 v252, 0x100000, v247
	v_add_u32_e32 v253, 0x180000, v247
.Lg1_loop:
	s_add_i32 s47, s46, 1
	s_cmp_ge_i32 s47, s3
	s_cbranch_scc1 .Lg1_cold
	s_add_i32 s46, s46, 2
	s_cmp_ge_i32 s46, s3
	s_cbranch_scc1 .Lg1_warm
	s_waitcnt lgkmcnt(7)
	v_mfma_f32_16x16x32_f16 v[148:151], v[176:179], v[164:167], v[148:151]
	v_mfma_f32_16x16x32_f16 v[112:115], v[176:179], v[168:171], v[112:115]
	v_mfma_f32_16x16x32_f16 v[96:99], v[176:179], v[172:175], v[96:99]
	v_mfma_f32_16x16x32_f16 v[80:83], v[176:179], v[192:195], v[80:83]
	s_waitcnt vmcnt(7)
	ds_write_b128 v254, v[124:127]
	global_load_dwordx4 v[124:127], v246, s[30:31] offset:256
	s_waitcnt lgkmcnt(7)
	v_mfma_f32_16x16x32_f16 v[128:131], v[180:183], v[164:167], v[128:131]
	v_mfma_f32_16x16x32_f16 v[108:111], v[180:183], v[168:171], v[108:111]
	v_mfma_f32_16x16x32_f16 v[92:95], v[180:183], v[172:175], v[92:95]
	v_mfma_f32_16x16x32_f16 v[76:79], v[180:183], v[192:195], v[76:79]
	s_waitcnt vmcnt(7)
	ds_write_b128 v254, v[132:135] offset:1024
	global_load_dwordx4 v[132:135], v248, s[30:31] offset:256
	s_waitcnt lgkmcnt(7)
	v_mfma_f32_16x16x32_f16 v[120:123], v[184:187], v[164:167], v[120:123]
	v_mfma_f32_16x16x32_f16 v[104:107], v[184:187], v[168:171], v[104:107]
	v_mfma_f32_16x16x32_f16 v[88:91], v[184:187], v[172:175], v[88:91]
	v_mfma_f32_16x16x32_f16 v[72:75], v[184:187], v[192:195], v[72:75]
	s_waitcnt vmcnt(7)
	ds_write_b128 v254, v[136:139] offset:2048
	global_load_dwordx4 v[136:139], v249, s[30:31] offset:256
	s_waitcnt lgkmcnt(7)
	v_mfma_f32_16x16x32_f16 v[116:119], v[188:191], v[164:167], v[116:119]
	v_mfma_f32_16x16x32_f16 v[100:103], v[188:191], v[168:171], v[100:103]
	v_mfma_f32_16x16x32_f16 v[84:87], v[188:191], v[172:175], v[84:87]
	v_mfma_f32_16x16x32_f16 v[68:71], v[188:191], v[192:195], v[68:71]
	s_waitcnt vmcnt(7)
	ds_write_b128 v254, v[140:143] offset:3072
	global_load_dwordx4 v[140:143], v250, s[30:31] offset:256
	ds_read_b128 v[164:167], v239
	ds_read_b128 v[168:171], v239 offset:256
	ds_read_b128 v[172:175], v239 offset:512
	ds_read_b128 v[192:195], v239 offset:768
	s_waitcnt lgkmcnt(11)
	v_mfma_f32_16x16x32_f16 v[64:67], v[176:179], v[196:199], v[64:67]
	s_waitcnt lgkmcnt(10)
	v_mfma_f32_16x16x32_f16 v[48:51], v[176:179], v[200:203], v[48:51]
	s_waitcnt lgkmcnt(9)
	v_mfma_f32_16x16x32_f16 v[30:33], v[176:179], v[204:207], v[30:33]
	s_waitcnt lgkmcnt(8)
	v_mfma_f32_16x16x32_f16 v[14:17], v[176:179], v[208:211], v[14:17]
	ds_read_b128 v[176:179], v237
	s_waitcnt vmcnt(7)
	ds_write_b128 v255, v[144:147]
	global_load_dwordx4 v[144:147], v247, s[38:39] offset:256
	v_mfma_f32_16x16x32_f16 v[60:63], v[180:183], v[196:199], v[60:63]
	v_mfma_f32_16x16x32_f16 v[44:47], v[180:183], v[200:203], v[44:47]
	v_mfma_f32_16x16x32_f16 v[26:29], v[180:183], v[204:207], v[26:29]
	v_mfma_f32_16x16x32_f16 v[10:13], v[180:183], v[208:211], v[10:13]
	ds_read_b128 v[180:183], v237 offset:256
	s_waitcnt vmcnt(7)
	ds_write_b128 v255, v[152:155] offset:1024
	global_load_dwordx4 v[152:155], v251, s[38:39] offset:256
	v_mfma_f32_16x16x32_f16 v[56:59], v[184:187], v[196:199], v[56:59]
	v_mfma_f32_16x16x32_f16 v[40:43], v[184:187], v[200:203], v[40:43]
	v_mfma_f32_16x16x32_f16 v[22:25], v[184:187], v[204:207], v[22:25]
	v_mfma_f32_16x16x32_f16 v[6:9], v[184:187], v[208:211], v[6:9]
	ds_read_b128 v[184:187], v237 offset:512
	s_waitcnt vmcnt(7)
	ds_write_b128 v255, v[156:159] offset:2048
	global_load_dwordx4 v[156:159], v252, s[38:39] offset:256
	v_mfma_f32_16x16x32_f16 v[52:55], v[188:191], v[196:199], v[52:55]
	v_mfma_f32_16x16x32_f16 v[36:39], v[188:191], v[200:203], v[36:39]
	v_mfma_f32_16x16x32_f16 v[18:21], v[188:191], v[204:207], v[18:21]
	v_mfma_f32_16x16x32_f16 v[2:5], v[188:191], v[208:211], v[2:5]
	ds_read_b128 v[188:191], v237 offset:768
	s_waitcnt vmcnt(7)
	ds_write_b128 v255, v[160:163] offset:3072
	global_load_dwordx4 v[160:163], v253, s[38:39] offset:256
	ds_read_b128 v[196:199], v239 offset:1024
	ds_read_b128 v[200:203], v239 offset:1280
	ds_read_b128 v[204:207], v239 offset:1536
	ds_read_b128 v[208:211], v239 offset:1792
	s_waitcnt lgkmcnt(11)
	v_mfma_f32_16x16x32_f16 v[148:151], v[176:179], v[164:167], v[148:151]
	v_mfma_f32_16x16x32_f16 v[112:115], v[176:179], v[168:171], v[112:115]
	v_mfma_f32_16x16x32_f16 v[96:99], v[176:179], v[172:175], v[96:99]
	v_mfma_f32_16x16x32_f16 v[80:83], v[176:179], v[192:195], v[80:83]
	s_waitcnt lgkmcnt(9)
	v_mfma_f32_16x16x32_f16 v[128:131], v[180:183], v[164:167], v[128:131]
	v_mfma_f32_16x16x32_f16 v[108:111], v[180:183], v[168:171], v[108:111]
	v_mfma_f32_16x16x32_f16 v[92:95], v[180:183], v[172:175], v[92:95]
	v_mfma_f32_16x16x32_f16 v[76:79], v[180:183], v[192:195], v[76:79]
	s_waitcnt lgkmcnt(7)
	v_mfma_f32_16x16x32_f16 v[120:123], v[184:187], v[164:167], v[120:123]
	v_mfma_f32_16x16x32_f16 v[104:107], v[184:187], v[168:171], v[104:107]
	v_mfma_f32_16x16x32_f16 v[88:91], v[184:187], v[172:175], v[88:91]
	v_mfma_f32_16x16x32_f16 v[72:75], v[184:187], v[192:195], v[72:75]
	s_waitcnt lgkmcnt(5)
	v_mfma_f32_16x16x32_f16 v[116:119], v[188:191], v[164:167], v[116:119]
	v_mfma_f32_16x16x32_f16 v[100:103], v[188:191], v[168:171], v[100:103]
	v_mfma_f32_16x16x32_f16 v[84:87], v[188:191], v[172:175], v[84:87]
	v_mfma_f32_16x16x32_f16 v[68:71], v[188:191], v[192:195], v[68:71]
	s_waitcnt lgkmcnt(0)
	s_barrier
	ds_read_b128 v[164:167], v238
	ds_read_b128 v[168:171], v238 offset:256
	ds_read_b128 v[172:175], v238 offset:512
	ds_read_b128 v[192:195], v238 offset:768
	v_mfma_f32_16x16x32_f16 v[64:67], v[176:179], v[196:199], v[64:67]
	v_mfma_f32_16x16x32_f16 v[48:51], v[176:179], v[200:203], v[48:51]
	v_mfma_f32_16x16x32_f16 v[30:33], v[176:179], v[204:207], v[30:33]
	v_mfma_f32_16x16x32_f16 v[14:17], v[176:179], v[208:211], v[14:17]
	ds_read_b128 v[176:179], v236
	v_mfma_f32_16x16x32_f16 v[60:63], v[180:183], v[196:199], v[60:63]
	v_mfma_f32_16x16x32_f16 v[44:47], v[180:183], v[200:203], v[44:47]
	v_mfma_f32_16x16x32_f16 v[26:29], v[180:183], v[204:207], v[26:29]
	v_mfma_f32_16x16x32_f16 v[10:13], v[180:183], v[208:211], v[10:13]
	ds_read_b128 v[180:183], v236 offset:256
	v_mfma_f32_16x16x32_f16 v[56:59], v[184:187], v[196:199], v[56:59]
	v_mfma_f32_16x16x32_f16 v[40:43], v[184:187], v[200:203], v[40:43]
	v_mfma_f32_16x16x32_f16 v[22:25], v[184:187], v[204:207], v[22:25]
	v_mfma_f32_16x16x32_f16 v[6:9], v[184:187], v[208:211], v[6:9]
	ds_read_b128 v[184:187], v236 offset:512
	v_mfma_f32_16x16x32_f16 v[52:55], v[188:191], v[196:199], v[52:55]
	v_mfma_f32_16x16x32_f16 v[36:39], v[188:191], v[200:203], v[36:39]
	v_mfma_f32_16x16x32_f16 v[18:21], v[188:191], v[204:207], v[18:21]
	v_mfma_f32_16x16x32_f16 v[2:5], v[188:191], v[208:211], v[2:5]
	ds_read_b128 v[188:191], v236 offset:768
	ds_read_b128 v[196:199], v238 offset:1024
	ds_read_b128 v[200:203], v238 offset:1280
	ds_read_b128 v[204:207], v238 offset:1536
	ds_read_b128 v[208:211], v238 offset:1792
	v_xor_b32_e32 v239, 0x8000, v239
	v_xor_b32_e32 v237, 0x8000, v237
	v_xor_b32_e32 v254, 0x8000, v254
	v_xor_b32_e32 v255, 0x8000, v255
	v_xor_b32_e32 v236, 0x8000, v236
	v_xor_b32_e32 v238, 0x8000, v238
	s_addk_i32 s45, 0x800
	s_add_u32 s30, s30, 0x80
	s_addc_u32 s31, s31, 0
	s_add_u32 s38, s38, 0x80
	s_addc_u32 s39, s39, 0
	s_mov_b32 s46, s47
	s_branch .Lg1_loop
.Lg1_warm:
	s_waitcnt lgkmcnt(7)
	v_mfma_f32_16x16x32_f16 v[148:151], v[176:179], v[164:167], v[148:151]
	v_mfma_f32_16x16x32_f16 v[112:115], v[176:179], v[168:171], v[112:115]
	v_mfma_f32_16x16x32_f16 v[96:99], v[176:179], v[172:175], v[96:99]
	v_mfma_f32_16x16x32_f16 v[80:83], v[176:179], v[192:195], v[80:83]
	s_waitcnt vmcnt(7)
	ds_write_b128 v254, v[124:127]
	s_waitcnt lgkmcnt(7)
	v_mfma_f32_16x16x32_f16 v[128:131], v[180:183], v[164:167], v[128:131]
	v_mfma_f32_16x16x32_f16 v[108:111], v[180:183], v[168:171], v[108:111]
	v_mfma_f32_16x16x32_f16 v[92:95], v[180:183], v[172:175], v[92:95]
	v_mfma_f32_16x16x32_f16 v[76:79], v[180:183], v[192:195], v[76:79]
	s_waitcnt vmcnt(6)
	ds_write_b128 v254, v[132:135] offset:1024
	s_waitcnt lgkmcnt(7)
	v_mfma_f32_16x16x32_f16 v[120:123], v[184:187], v[164:167], v[120:123]
	v_mfma_f32_16x16x32_f16 v[104:107], v[184:187], v[168:171], v[104:107]
	v_mfma_f32_16x16x32_f16 v[88:91], v[184:187], v[172:175], v[88:91]
	v_mfma_f32_16x16x32_f16 v[72:75], v[184:187], v[192:195], v[72:75]
	s_waitcnt vmcnt(5)
	ds_write_b128 v254, v[136:139] offset:2048
	s_waitcnt lgkmcnt(7)
	v_mfma_f32_16x16x32_f16 v[116:119], v[188:191], v[164:167], v[116:119]
	v_mfma_f32_16x16x32_f16 v[100:103], v[188:191], v[168:171], v[100:103]
	v_mfma_f32_16x16x32_f16 v[84:87], v[188:191], v[172:175], v[84:87]
	v_mfma_f32_16x16x32_f16 v[68:71], v[188:191], v[192:195], v[68:71]
	s_waitcnt vmcnt(4)
	ds_write_b128 v254, v[140:143] offset:3072
	ds_read_b128 v[164:167], v239
	ds_read_b128 v[168:171], v239 offset:256
	ds_read_b128 v[172:175], v239 offset:512
	ds_read_b128 v[192:195], v239 offset:768
	s_waitcnt lgkmcnt(11)
	v_mfma_f32_16x16x32_f16 v[64:67], v[176:179], v[196:199], v[64:67]
	s_waitcnt lgkmcnt(10)
	v_mfma_f32_16x16x32_f16 v[48:51], v[176:179], v[200:203], v[48:51]
	s_waitcnt lgkmcnt(9)
	v_mfma_f32_16x16x32_f16 v[30:33], v[176:179], v[204:207], v[30:33]
	s_waitcnt lgkmcnt(8)
	v_mfma_f32_16x16x32_f16 v[14:17], v[176:179], v[208:211], v[14:17]
	ds_read_b128 v[176:179], v237
	s_waitcnt vmcnt(3)
	ds_write_b128 v255, v[144:147]
	v_mfma_f32_16x16x32_f16 v[60:63], v[180:183], v[196:199], v[60:63]
	v_mfma_f32_16x16x32_f16 v[44:47], v[180:183], v[200:203], v[44:47]
	v_mfma_f32_16x16x32_f16 v[26:29], v[180:183], v[204:207], v[26:29]
	v_mfma_f32_16x16x32_f16 v[10:13], v[180:183], v[208:211], v[10:13]
	ds_read_b128 v[180:183], v237 offset:256
	s_waitcnt vmcnt(2)
	ds_write_b128 v255, v[152:155] offset:1024
	v_mfma_f32_16x16x32_f16 v[56:59], v[184:187], v[196:199], v[56:59]
	v_mfma_f32_16x16x32_f16 v[40:43], v[184:187], v[200:203], v[40:43]
	v_mfma_f32_16x16x32_f16 v[22:25], v[184:187], v[204:207], v[22:25]
	v_mfma_f32_16x16x32_f16 v[6:9], v[184:187], v[208:211], v[6:9]
	ds_read_b128 v[184:187], v237 offset:512
	s_waitcnt vmcnt(1)
	ds_write_b128 v255, v[156:159] offset:2048
	v_mfma_f32_16x16x32_f16 v[52:55], v[188:191], v[196:199], v[52:55]
	v_mfma_f32_16x16x32_f16 v[36:39], v[188:191], v[200:203], v[36:39]
	v_mfma_f32_16x16x32_f16 v[18:21], v[188:191], v[204:207], v[18:21]
	v_mfma_f32_16x16x32_f16 v[2:5], v[188:191], v[208:211], v[2:5]
	ds_read_b128 v[188:191], v237 offset:768
	s_waitcnt vmcnt(0)
	ds_write_b128 v255, v[160:163] offset:3072
	ds_read_b128 v[196:199], v239 offset:1024
	ds_read_b128 v[200:203], v239 offset:1280
	ds_read_b128 v[204:207], v239 offset:1536
	ds_read_b128 v[208:211], v239 offset:1792
	s_waitcnt lgkmcnt(11)
	v_mfma_f32_16x16x32_f16 v[148:151], v[176:179], v[164:167], v[148:151]
	v_mfma_f32_16x16x32_f16 v[112:115], v[176:179], v[168:171], v[112:115]
	v_mfma_f32_16x16x32_f16 v[96:99], v[176:179], v[172:175], v[96:99]
	v_mfma_f32_16x16x32_f16 v[80:83], v[176:179], v[192:195], v[80:83]
	s_waitcnt lgkmcnt(9)
	v_mfma_f32_16x16x32_f16 v[128:131], v[180:183], v[164:167], v[128:131]
	v_mfma_f32_16x16x32_f16 v[108:111], v[180:183], v[168:171], v[108:111]
	v_mfma_f32_16x16x32_f16 v[92:95], v[180:183], v[172:175], v[92:95]
	v_mfma_f32_16x16x32_f16 v[76:79], v[180:183], v[192:195], v[76:79]
	s_waitcnt lgkmcnt(7)
	v_mfma_f32_16x16x32_f16 v[120:123], v[184:187], v[164:167], v[120:123]
	v_mfma_f32_16x16x32_f16 v[104:107], v[184:187], v[168:171], v[104:107]
	v_mfma_f32_16x16x32_f16 v[88:91], v[184:187], v[172:175], v[88:91]
	v_mfma_f32_16x16x32_f16 v[72:75], v[184:187], v[192:195], v[72:75]
	s_waitcnt lgkmcnt(5)
	v_mfma_f32_16x16x32_f16 v[116:119], v[188:191], v[164:167], v[116:119]
	v_mfma_f32_16x16x32_f16 v[100:103], v[188:191], v[168:171], v[100:103]
	v_mfma_f32_16x16x32_f16 v[84:87], v[188:191], v[172:175], v[84:87]
	v_mfma_f32_16x16x32_f16 v[68:71], v[188:191], v[192:195], v[68:71]
	s_waitcnt lgkmcnt(0)
	s_barrier
	ds_read_b128 v[164:167], v238
	ds_read_b128 v[168:171], v238 offset:256
	ds_read_b128 v[172:175], v238 offset:512
	ds_read_b128 v[192:195], v238 offset:768
	v_mfma_f32_16x16x32_f16 v[64:67], v[176:179], v[196:199], v[64:67]
	v_mfma_f32_16x16x32_f16 v[48:51], v[176:179], v[200:203], v[48:51]
	v_mfma_f32_16x16x32_f16 v[30:33], v[176:179], v[204:207], v[30:33]
	v_mfma_f32_16x16x32_f16 v[14:17], v[176:179], v[208:211], v[14:17]
	ds_read_b128 v[176:179], v236
	v_mfma_f32_16x16x32_f16 v[60:63], v[180:183], v[196:199], v[60:63]
	v_mfma_f32_16x16x32_f16 v[44:47], v[180:183], v[200:203], v[44:47]
	v_mfma_f32_16x16x32_f16 v[26:29], v[180:183], v[204:207], v[26:29]
	v_mfma_f32_16x16x32_f16 v[10:13], v[180:183], v[208:211], v[10:13]
	ds_read_b128 v[180:183], v236 offset:256
	v_mfma_f32_16x16x32_f16 v[56:59], v[184:187], v[196:199], v[56:59]
	v_mfma_f32_16x16x32_f16 v[40:43], v[184:187], v[200:203], v[40:43]
	v_mfma_f32_16x16x32_f16 v[22:25], v[184:187], v[204:207], v[22:25]
	v_mfma_f32_16x16x32_f16 v[6:9], v[184:187], v[208:211], v[6:9]
	ds_read_b128 v[184:187], v236 offset:512
	v_mfma_f32_16x16x32_f16 v[52:55], v[188:191], v[196:199], v[52:55]
	v_mfma_f32_16x16x32_f16 v[36:39], v[188:191], v[200:203], v[36:39]
	v_mfma_f32_16x16x32_f16 v[18:21], v[188:191], v[204:207], v[18:21]
	v_mfma_f32_16x16x32_f16 v[2:5], v[188:191], v[208:211], v[2:5]
	ds_read_b128 v[188:191], v236 offset:768
	ds_read_b128 v[196:199], v238 offset:1024
	ds_read_b128 v[200:203], v238 offset:1280
	ds_read_b128 v[204:207], v238 offset:1536
	ds_read_b128 v[208:211], v238 offset:1792
	v_xor_b32_e32 v239, 0x8000, v239
	v_xor_b32_e32 v237, 0x8000, v237
	v_xor_b32_e32 v254, 0x8000, v254
	v_xor_b32_e32 v255, 0x8000, v255
	v_xor_b32_e32 v236, 0x8000, v236
	v_xor_b32_e32 v238, 0x8000, v238
	s_addk_i32 s45, 0x800
	s_mov_b32 s46, s47
	s_branch .Lg1_loop

.LBB0_136:
	v_add3_u32 v238, v232, v233, v236
	v_add3_u32 v239, v234, v233, v237
	v_add3_u32 v236, v232, v235, v236
	v_add3_u32 v237, v234, v235, v237
	v_add_u32_e32 v236, 0x10000, v236
	v_add_u32_e32 v237, 0x10000, v237
	v_add_u32_e32 v254, 0x8000, v229
	v_add_u32_e32 v255, 0x8000, v230
	ds_read_b128 v[164:167], v238
	ds_read_b128 v[168:171], v238 offset:256
	ds_read_b128 v[172:175], v238 offset:512
	ds_read_b128 v[192:195], v238 offset:768
	ds_read_b128 v[176:179], v236
	ds_read_b128 v[180:183], v236 offset:256
	ds_read_b128 v[184:187], v236 offset:512
	ds_read_b128 v[188:191], v236 offset:768
	ds_read_b128 v[196:199], v238 offset:1024
	ds_read_b128 v[200:203], v238 offset:1280
	ds_read_b128 v[204:207], v238 offset:1536
	ds_read_b128 v[208:211], v238 offset:1792
	s_nop 0
	v_xor_b32_e32 v238, 0x8000, v238
	v_xor_b32_e32 v236, 0x8000, v236
	v_add_u32_e32 v246, v227, v228
	v_add_u32_e32 v247, v227, v231
	v_lshlrev_b32_e32 v246, 1, v246
	v_lshlrev_b32_e32 v247, 1, v247
	v_add_u32_e32 v248, 0x20000, v246
	v_add_u32_e32 v249, 0x40000, v246
	v_add_u32_e32 v250, 0x60000, v246
	v_add_u32_e32 v251, 0x20000, v247
	v_add_u32_e32 v252, 0x40000, v247
	v_add_u32_e32 v253, 0x60000, v247
.Lg2_loop:
	s_add_i32 s43, s42, 1
	s_cmp_ge_i32 s43, s3
	s_cbranch_scc1 .Lg2_cold
	s_add_i32 s42, s42, 2
	s_cmp_ge_i32 s42, s3
	s_cbranch_scc1 .Lg2_warm
	s_waitcnt lgkmcnt(7)
	v_mfma_f32_16x16x32_f16 v[156:159], v[176:179], v[164:167], v[156:159]
	v_mfma_f32_16x16x32_f16 v[112:115], v[176:179], v[168:171], v[112:115]
	v_mfma_f32_16x16x32_f16 v[96:99], v[176:179], v[172:175], v[96:99]
	v_mfma_f32_16x16x32_f16 v[80:83], v[176:179], v[192:195], v[80:83]
	s_waitcnt vmcnt(7)
	ds_write_b128 v254, v[116:119]
	global_load_dwordx4 v[116:119], v246, s[30:31] offset:256
	s_waitcnt lgkmcnt(7)
	v_mfma_f32_16x16x32_f16 v[148:151], v[180:183], v[164:167], v[148:151]
	v_mfma_f32_16x16x32_f16 v[108:111], v[180:183], v[168:171], v[108:111]
	v_mfma_f32_16x16x32_f16 v[92:95], v[180:183], v[172:175], v[92:95]
	v_mfma_f32_16x16x32_f16 v[76:79], v[180:183], v[192:195], v[76:79]
	s_waitcnt vmcnt(7)
	ds_write_b128 v254, v[120:123] offset:1024
	global_load_dwordx4 v[120:123], v248, s[30:31] offset:256
	s_waitcnt lgkmcnt(7)
	v_mfma_f32_16x16x32_f16 v[132:135], v[184:187], v[164:167], v[132:135]
	v_mfma_f32_16x16x32_f16 v[104:107], v[184:187], v[168:171], v[104:107]
	v_mfma_f32_16x16x32_f16 v[88:91], v[184:187], v[172:175], v[88:91]
	v_mfma_f32_16x16x32_f16 v[72:75], v[184:187], v[192:195], v[72:75]
	s_waitcnt vmcnt(7)
	ds_write_b128 v254, v[128:131] offset:2048
	global_load_dwordx4 v[128:131], v249, s[30:31] offset:256
	s_waitcnt lgkmcnt(7)
	v_mfma_f32_16x16x32_f16 v[124:127], v[188:191], v[164:167], v[124:127]
	v_mfma_f32_16x16x32_f16 v[100:103], v[188:191], v[168:171], v[100:103]
	v_mfma_f32_16x16x32_f16 v[84:87], v[188:191], v[172:175], v[84:87]
	v_mfma_f32_16x16x32_f16 v[68:71], v[188:191], v[192:195], v[68:71]
	s_waitcnt vmcnt(7)
	ds_write_b128 v254, v[136:139] offset:3072
	global_load_dwordx4 v[136:139], v250, s[30:31] offset:256
	ds_read_b128 v[164:167], v239
	ds_read_b128 v[168:171], v239 offset:256
	ds_read_b128 v[172:175], v239 offset:512
	ds_read_b128 v[192:195], v239 offset:768
	s_waitcnt lgkmcnt(11)
	v_mfma_f32_16x16x32_f16 v[64:67], v[176:179], v[196:199], v[64:67]
	s_waitcnt lgkmcnt(10)
	v_mfma_f32_16x16x32_f16 v[48:51], v[176:179], v[200:203], v[48:51]
	s_waitcnt lgkmcnt(9)
	v_mfma_f32_16x16x32_f16 v[30:33], v[176:179], v[204:207], v[30:33]
	s_waitcnt lgkmcnt(8)
	v_mfma_f32_16x16x32_f16 v[14:17], v[176:179], v[208:211], v[14:17]
	ds_read_b128 v[176:179], v237
	s_waitcnt vmcnt(7)
	ds_write_b128 v255, v[140:143]
	global_load_dwordx4 v[140:143], v247, s[38:39] offset:256
	v_mfma_f32_16x16x32_f16 v[60:63], v[180:183], v[196:199], v[60:63]
	v_mfma_f32_16x16x32_f16 v[44:47], v[180:183], v[200:203], v[44:47]
	v_mfma_f32_16x16x32_f16 v[26:29], v[180:183], v[204:207], v[26:29]
	v_mfma_f32_16x16x32_f16 v[10:13], v[180:183], v[208:211], v[10:13]
	ds_read_b128 v[180:183], v237 offset:256
	s_waitcnt vmcnt(7)
	ds_write_b128 v255, v[144:147] offset:1024
	global_load_dwordx4 v[144:147], v251, s[38:39] offset:256
	v_mfma_f32_16x16x32_f16 v[56:59], v[184:187], v[196:199], v[56:59]
	v_mfma_f32_16x16x32_f16 v[40:43], v[184:187], v[200:203], v[40:43]
	v_mfma_f32_16x16x32_f16 v[22:25], v[184:187], v[204:207], v[22:25]
	v_mfma_f32_16x16x32_f16 v[6:9], v[184:187], v[208:211], v[6:9]
	ds_read_b128 v[184:187], v237 offset:512
	s_waitcnt vmcnt(7)
	ds_write_b128 v255, v[152:155] offset:2048
	global_load_dwordx4 v[152:155], v252, s[38:39] offset:256
	v_mfma_f32_16x16x32_f16 v[52:55], v[188:191], v[196:199], v[52:55]
	v_mfma_f32_16x16x32_f16 v[36:39], v[188:191], v[200:203], v[36:39]
	v_mfma_f32_16x16x32_f16 v[18:21], v[188:191], v[204:207], v[18:21]
	v_mfma_f32_16x16x32_f16 v[2:5], v[188:191], v[208:211], v[2:5]
	ds_read_b128 v[188:191], v237 offset:768
	s_waitcnt vmcnt(7)
	ds_write_b128 v255, v[160:163] offset:3072
	global_load_dwordx4 v[160:163], v253, s[38:39] offset:256
	ds_read_b128 v[196:199], v239 offset:1024
	ds_read_b128 v[200:203], v239 offset:1280
	ds_read_b128 v[204:207], v239 offset:1536
	ds_read_b128 v[208:211], v239 offset:1792
	s_waitcnt lgkmcnt(11)
	v_mfma_f32_16x16x32_f16 v[156:159], v[176:179], v[164:167], v[156:159]
	v_mfma_f32_16x16x32_f16 v[112:115], v[176:179], v[168:171], v[112:115]
	v_mfma_f32_16x16x32_f16 v[96:99], v[176:179], v[172:175], v[96:99]
	v_mfma_f32_16x16x32_f16 v[80:83], v[176:179], v[192:195], v[80:83]
	s_waitcnt lgkmcnt(9)
	v_mfma_f32_16x16x32_f16 v[148:151], v[180:183], v[164:167], v[148:151]
	v_mfma_f32_16x16x32_f16 v[108:111], v[180:183], v[168:171], v[108:111]
	v_mfma_f32_16x16x32_f16 v[92:95], v[180:183], v[172:175], v[92:95]
	v_mfma_f32_16x16x32_f16 v[76:79], v[180:183], v[192:195], v[76:79]
	s_waitcnt lgkmcnt(7)
	v_mfma_f32_16x16x32_f16 v[132:135], v[184:187], v[164:167], v[132:135]
	v_mfma_f32_16x16x32_f16 v[104:107], v[184:187], v[168:171], v[104:107]
	v_mfma_f32_16x16x32_f16 v[88:91], v[184:187], v[172:175], v[88:91]
	v_mfma_f32_16x16x32_f16 v[72:75], v[184:187], v[192:195], v[72:75]
	s_waitcnt lgkmcnt(5)
	v_mfma_f32_16x16x32_f16 v[124:127], v[188:191], v[164:167], v[124:127]
	v_mfma_f32_16x16x32_f16 v[100:103], v[188:191], v[168:171], v[100:103]
	v_mfma_f32_16x16x32_f16 v[84:87], v[188:191], v[172:175], v[84:87]
	v_mfma_f32_16x16x32_f16 v[68:71], v[188:191], v[192:195], v[68:71]
	s_waitcnt lgkmcnt(0)
	s_barrier
	ds_read_b128 v[164:167], v238
	ds_read_b128 v[168:171], v238 offset:256
	ds_read_b128 v[172:175], v238 offset:512
	ds_read_b128 v[192:195], v238 offset:768
	v_mfma_f32_16x16x32_f16 v[64:67], v[176:179], v[196:199], v[64:67]
	v_mfma_f32_16x16x32_f16 v[48:51], v[176:179], v[200:203], v[48:51]
	v_mfma_f32_16x16x32_f16 v[30:33], v[176:179], v[204:207], v[30:33]
	v_mfma_f32_16x16x32_f16 v[14:17], v[176:179], v[208:211], v[14:17]
	ds_read_b128 v[176:179], v236
	v_mfma_f32_16x16x32_f16 v[60:63], v[180:183], v[196:199], v[60:63]
	v_mfma_f32_16x16x32_f16 v[44:47], v[180:183], v[200:203], v[44:47]
	v_mfma_f32_16x16x32_f16 v[26:29], v[180:183], v[204:207], v[26:29]
	v_mfma_f32_16x16x32_f16 v[10:13], v[180:183], v[208:211], v[10:13]
	ds_read_b128 v[180:183], v236 offset:256
	v_mfma_f32_16x16x32_f16 v[56:59], v[184:187], v[196:199], v[56:59]
	v_mfma_f32_16x16x32_f16 v[40:43], v[184:187], v[200:203], v[40:43]
	v_mfma_f32_16x16x32_f16 v[22:25], v[184:187], v[204:207], v[22:25]
	v_mfma_f32_16x16x32_f16 v[6:9], v[184:187], v[208:211], v[6:9]
	ds_read_b128 v[184:187], v236 offset:512
	v_mfma_f32_16x16x32_f16 v[52:55], v[188:191], v[196:199], v[52:55]
	v_mfma_f32_16x16x32_f16 v[36:39], v[188:191], v[200:203], v[36:39]
	v_mfma_f32_16x16x32_f16 v[18:21], v[188:191], v[204:207], v[18:21]
	v_mfma_f32_16x16x32_f16 v[2:5], v[188:191], v[208:211], v[2:5]
	ds_read_b128 v[188:191], v236 offset:768
	ds_read_b128 v[196:199], v238 offset:1024
	ds_read_b128 v[200:203], v238 offset:1280
	ds_read_b128 v[204:207], v238 offset:1536
	ds_read_b128 v[208:211], v238 offset:1792
	v_xor_b32_e32 v239, 0x8000, v239
	v_xor_b32_e32 v237, 0x8000, v237
	v_xor_b32_e32 v254, 0x8000, v254
	v_xor_b32_e32 v255, 0x8000, v255
	v_xor_b32_e32 v236, 0x8000, v236
	v_xor_b32_e32 v238, 0x8000, v238
	s_addk_i32 s23, 0x800
	s_add_u32 s30, s30, 0x80
	s_addc_u32 s31, s31, 0
	s_add_u32 s38, s38, 0x80
	s_addc_u32 s39, s39, 0
	s_mov_b32 s42, s43
	s_branch .Lg2_loop
.Lg2_warm:
	s_waitcnt lgkmcnt(7)
	v_mfma_f32_16x16x32_f16 v[156:159], v[176:179], v[164:167], v[156:159]
	v_mfma_f32_16x16x32_f16 v[112:115], v[176:179], v[168:171], v[112:115]
	v_mfma_f32_16x16x32_f16 v[96:99], v[176:179], v[172:175], v[96:99]
	v_mfma_f32_16x16x32_f16 v[80:83], v[176:179], v[192:195], v[80:83]
	s_waitcnt vmcnt(7)
	ds_write_b128 v254, v[116:119]
	s_waitcnt lgkmcnt(7)
	v_mfma_f32_16x16x32_f16 v[148:151], v[180:183], v[164:167], v[148:151]
	v_mfma_f32_16x16x32_f16 v[108:111], v[180:183], v[168:171], v[108:111]
	v_mfma_f32_16x16x32_f16 v[92:95], v[180:183], v[172:175], v[92:95]
	v_mfma_f32_16x16x32_f16 v[76:79], v[180:183], v[192:195], v[76:79]
	s_waitcnt vmcnt(6)
	ds_write_b128 v254, v[120:123] offset:1024
	s_waitcnt lgkmcnt(7)
	v_mfma_f32_16x16x32_f16 v[132:135], v[184:187], v[164:167], v[132:135]
	v_mfma_f32_16x16x32_f16 v[104:107], v[184:187], v[168:171], v[104:107]
	v_mfma_f32_16x16x32_f16 v[88:91], v[184:187], v[172:175], v[88:91]
	v_mfma_f32_16x16x32_f16 v[72:75], v[184:187], v[192:195], v[72:75]
	s_waitcnt vmcnt(5)
	ds_write_b128 v254, v[128:131] offset:2048
	s_waitcnt lgkmcnt(7)
	v_mfma_f32_16x16x32_f16 v[124:127], v[188:191], v[164:167], v[124:127]
	v_mfma_f32_16x16x32_f16 v[100:103], v[188:191], v[168:171], v[100:103]
	v_mfma_f32_16x16x32_f16 v[84:87], v[188:191], v[172:175], v[84:87]
	v_mfma_f32_16x16x32_f16 v[68:71], v[188:191], v[192:195], v[68:71]
	s_waitcnt vmcnt(4)
	ds_write_b128 v254, v[136:139] offset:3072
	ds_read_b128 v[164:167], v239
	ds_read_b128 v[168:171], v239 offset:256
	ds_read_b128 v[172:175], v239 offset:512
	ds_read_b128 v[192:195], v239 offset:768
	s_waitcnt lgkmcnt(11)
	v_mfma_f32_16x16x32_f16 v[64:67], v[176:179], v[196:199], v[64:67]
	s_waitcnt lgkmcnt(10)
	v_mfma_f32_16x16x32_f16 v[48:51], v[176:179], v[200:203], v[48:51]
	s_waitcnt lgkmcnt(9)
	v_mfma_f32_16x16x32_f16 v[30:33], v[176:179], v[204:207], v[30:33]
	s_waitcnt lgkmcnt(8)
	v_mfma_f32_16x16x32_f16 v[14:17], v[176:179], v[208:211], v[14:17]
	ds_read_b128 v[176:179], v237
	s_waitcnt vmcnt(3)
	ds_write_b128 v255, v[140:143]
	v_mfma_f32_16x16x32_f16 v[60:63], v[180:183], v[196:199], v[60:63]
	v_mfma_f32_16x16x32_f16 v[44:47], v[180:183], v[200:203], v[44:47]
	v_mfma_f32_16x16x32_f16 v[26:29], v[180:183], v[204:207], v[26:29]
	v_mfma_f32_16x16x32_f16 v[10:13], v[180:183], v[208:211], v[10:13]
	ds_read_b128 v[180:183], v237 offset:256
	s_waitcnt vmcnt(2)
	ds_write_b128 v255, v[144:147] offset:1024
	v_mfma_f32_16x16x32_f16 v[56:59], v[184:187], v[196:199], v[56:59]
	v_mfma_f32_16x16x32_f16 v[40:43], v[184:187], v[200:203], v[40:43]
	v_mfma_f32_16x16x32_f16 v[22:25], v[184:187], v[204:207], v[22:25]
	v_mfma_f32_16x16x32_f16 v[6:9], v[184:187], v[208:211], v[6:9]
	ds_read_b128 v[184:187], v237 offset:512
	s_waitcnt vmcnt(1)
	ds_write_b128 v255, v[152:155] offset:2048
	v_mfma_f32_16x16x32_f16 v[52:55], v[188:191], v[196:199], v[52:55]
	v_mfma_f32_16x16x32_f16 v[36:39], v[188:191], v[200:203], v[36:39]
	v_mfma_f32_16x16x32_f16 v[18:21], v[188:191], v[204:207], v[18:21]
	v_mfma_f32_16x16x32_f16 v[2:5], v[188:191], v[208:211], v[2:5]
	ds_read_b128 v[188:191], v237 offset:768
	s_waitcnt vmcnt(0)
	ds_write_b128 v255, v[160:163] offset:3072
	ds_read_b128 v[196:199], v239 offset:1024
	ds_read_b128 v[200:203], v239 offset:1280
	ds_read_b128 v[204:207], v239 offset:1536
	ds_read_b128 v[208:211], v239 offset:1792
	s_waitcnt lgkmcnt(11)
	v_mfma_f32_16x16x32_f16 v[156:159], v[176:179], v[164:167], v[156:159]
	v_mfma_f32_16x16x32_f16 v[112:115], v[176:179], v[168:171], v[112:115]
	v_mfma_f32_16x16x32_f16 v[96:99], v[176:179], v[172:175], v[96:99]
	v_mfma_f32_16x16x32_f16 v[80:83], v[176:179], v[192:195], v[80:83]
	s_waitcnt lgkmcnt(9)
	v_mfma_f32_16x16x32_f16 v[148:151], v[180:183], v[164:167], v[148:151]
	v_mfma_f32_16x16x32_f16 v[108:111], v[180:183], v[168:171], v[108:111]
	v_mfma_f32_16x16x32_f16 v[92:95], v[180:183], v[172:175], v[92:95]
	v_mfma_f32_16x16x32_f16 v[76:79], v[180:183], v[192:195], v[76:79]
	s_waitcnt lgkmcnt(7)
	v_mfma_f32_16x16x32_f16 v[132:135], v[184:187], v[164:167], v[132:135]
	v_mfma_f32_16x16x32_f16 v[104:107], v[184:187], v[168:171], v[104:107]
	v_mfma_f32_16x16x32_f16 v[88:91], v[184:187], v[172:175], v[88:91]
	v_mfma_f32_16x16x32_f16 v[72:75], v[184:187], v[192:195], v[72:75]
	s_waitcnt lgkmcnt(5)
	v_mfma_f32_16x16x32_f16 v[124:127], v[188:191], v[164:167], v[124:127]
	v_mfma_f32_16x16x32_f16 v[100:103], v[188:191], v[168:171], v[100:103]
	v_mfma_f32_16x16x32_f16 v[84:87], v[188:191], v[172:175], v[84:87]
	v_mfma_f32_16x16x32_f16 v[68:71], v[188:191], v[192:195], v[68:71]
	s_waitcnt lgkmcnt(0)
	s_barrier
	ds_read_b128 v[164:167], v238
	ds_read_b128 v[168:171], v238 offset:256
	ds_read_b128 v[172:175], v238 offset:512
	ds_read_b128 v[192:195], v238 offset:768
	v_mfma_f32_16x16x32_f16 v[64:67], v[176:179], v[196:199], v[64:67]
	v_mfma_f32_16x16x32_f16 v[48:51], v[176:179], v[200:203], v[48:51]
	v_mfma_f32_16x16x32_f16 v[30:33], v[176:179], v[204:207], v[30:33]
	v_mfma_f32_16x16x32_f16 v[14:17], v[176:179], v[208:211], v[14:17]
	ds_read_b128 v[176:179], v236
	v_mfma_f32_16x16x32_f16 v[60:63], v[180:183], v[196:199], v[60:63]
	v_mfma_f32_16x16x32_f16 v[44:47], v[180:183], v[200:203], v[44:47]
	v_mfma_f32_16x16x32_f16 v[26:29], v[180:183], v[204:207], v[26:29]
	v_mfma_f32_16x16x32_f16 v[10:13], v[180:183], v[208:211], v[10:13]
	ds_read_b128 v[180:183], v236 offset:256
	v_mfma_f32_16x16x32_f16 v[56:59], v[184:187], v[196:199], v[56:59]
	v_mfma_f32_16x16x32_f16 v[40:43], v[184:187], v[200:203], v[40:43]
	v_mfma_f32_16x16x32_f16 v[22:25], v[184:187], v[204:207], v[22:25]
	v_mfma_f32_16x16x32_f16 v[6:9], v[184:187], v[208:211], v[6:9]
	ds_read_b128 v[184:187], v236 offset:512
	v_mfma_f32_16x16x32_f16 v[52:55], v[188:191], v[196:199], v[52:55]
	v_mfma_f32_16x16x32_f16 v[36:39], v[188:191], v[200:203], v[36:39]
	v_mfma_f32_16x16x32_f16 v[18:21], v[188:191], v[204:207], v[18:21]
	v_mfma_f32_16x16x32_f16 v[2:5], v[188:191], v[208:211], v[2:5]
	ds_read_b128 v[188:191], v236 offset:768
	ds_read_b128 v[196:199], v238 offset:1024
	ds_read_b128 v[200:203], v238 offset:1280
	ds_read_b128 v[204:207], v238 offset:1536
	ds_read_b128 v[208:211], v238 offset:1792
	v_xor_b32_e32 v239, 0x8000, v239
	v_xor_b32_e32 v237, 0x8000, v237
	v_xor_b32_e32 v254, 0x8000, v254
	v_xor_b32_e32 v255, 0x8000, v255
	v_xor_b32_e32 v236, 0x8000, v236
	v_xor_b32_e32 v238, 0x8000, v238
	s_addk_i32 s23, 0x800
	s_mov_b32 s42, s43
	s_branch .Lg2_loop

.LBB0_142:
	s_waitcnt vmcnt(5)
	v_lshl_add_u32 v118, s2, 8, v35
	v_ashrrev_i32_e32 v119, 31, v118
	v_lshl_or_b32 v116, s22, 8, v226
	s_waitcnt vmcnt(1)
	s_add_i32 s3, s33, 1
	s_mul_i32 s23, s3, s41
	s_mul_hi_u32 s3, s3, s41
	s_add_u32 s38, s23, s37
	s_addc_u32 s39, s3, 0
	s_lshr_b64 s[30:31], s[38:39], 2
	s_and_b32 s3, s30, -8
	s_or_b32 s23, s3, s35
	s_mov_b32 s98, 0
	s_cmp_gt_i32 s23, 63
	s_cbranch_scc1 .Lnxk9_skip
	s_lshr_b32 s3, s23, 1
	s_lshl_b32 s3, s3, 2
	s_and_b32 s30, s38, 3
	s_or_b32 s3, s3, s30
	s_and_b32 s30, s23, 1
	s_lshl_b32 s30, s30, 3
	s_bfe_u32 s31, s38, 0x30002
	s_or_b32 s30, s30, s31
	s_lshl_b32 s3, s3, 19
	s_lshl_b32 s30, s30, 19
	s_add_u32 s98, s16, s3
	s_addc_u32 s99, s17, 0
	s_add_u32 s100, s24, s30
	s_addc_u32 s101, s40, 0
	s_sub_u32 s98, s98, 0
	s_subb_u32 s99, s99, 0
	s_sub_u32 s100, s100, 0
	s_subb_u32 s101, s101, 0
	v_add_u32_e32 v246, v227, v228
	v_add_u32_e32 v247, v227, v231
	v_lshlrev_b32_e32 v246, 1, v246
	v_lshlrev_b32_e32 v247, 1, v247
	v_add_u32_e32 v248, 0x20000, v246
	v_add_u32_e32 v249, 0x40000, v246
	v_add_u32_e32 v250, 0x60000, v246
	v_add_u32_e32 v251, 0x20000, v247
	v_add_u32_e32 v252, 0x40000, v247
	v_add_u32_e32 v253, 0x60000, v247
	global_load_dwordx4 v[164:167], v246, s[98:99]
	global_load_dwordx4 v[168:171], v248, s[98:99]
	global_load_dwordx4 v[172:175], v249, s[98:99]
	global_load_dwordx4 v[192:195], v250, s[98:99]
	global_load_dwordx4 v[176:179], v247, s[100:101]
	global_load_dwordx4 v[180:183], v251, s[100:101]
	global_load_dwordx4 v[184:187], v252, s[100:101]
	global_load_dwordx4 v[188:191], v253, s[100:101]
	s_mov_b32 s98, 1

.Lg3_loop:
	s_add_i32 s49, s48, 1
	s_cmp_ge_i32 s49, s3
	s_cbranch_scc1 .Lg3_cold
	s_add_i32 s48, s48, 2
	s_cmp_ge_i32 s48, s3
	s_cbranch_scc1 .Lg3_warm
	s_waitcnt lgkmcnt(7)
	v_mfma_f32_16x16x32_f16 v[148:151], v[176:179], v[164:167], v[148:151]
	v_mfma_f32_16x16x32_f16 v[112:115], v[176:179], v[168:171], v[112:115]
	v_mfma_f32_16x16x32_f16 v[96:99], v[176:179], v[172:175], v[96:99]
	v_mfma_f32_16x16x32_f16 v[80:83], v[176:179], v[192:195], v[80:83]
	s_waitcnt vmcnt(7)
	ds_write_b128 v254, v[124:127]
	global_load_dwordx4 v[124:127], v246, s[30:31] offset:256
	s_waitcnt lgkmcnt(7)
	v_mfma_f32_16x16x32_f16 v[128:131], v[180:183], v[164:167], v[128:131]
	v_mfma_f32_16x16x32_f16 v[108:111], v[180:183], v[168:171], v[108:111]
	v_mfma_f32_16x16x32_f16 v[92:95], v[180:183], v[172:175], v[92:95]
	v_mfma_f32_16x16x32_f16 v[76:79], v[180:183], v[192:195], v[76:79]
	s_waitcnt vmcnt(7)
	ds_write_b128 v254, v[132:135] offset:1024
	global_load_dwordx4 v[132:135], v248, s[30:31] offset:256
	s_waitcnt lgkmcnt(7)
	v_mfma_f32_16x16x32_f16 v[120:123], v[184:187], v[164:167], v[120:123]
	v_mfma_f32_16x16x32_f16 v[104:107], v[184:187], v[168:171], v[104:107]
	v_mfma_f32_16x16x32_f16 v[88:91], v[184:187], v[172:175], v[88:91]
	v_mfma_f32_16x16x32_f16 v[72:75], v[184:187], v[192:195], v[72:75]
	s_waitcnt vmcnt(7)
	ds_write_b128 v254, v[136:139] offset:2048
	global_load_dwordx4 v[136:139], v249, s[30:31] offset:256
	s_waitcnt lgkmcnt(7)
	v_mfma_f32_16x16x32_f16 v[116:119], v[188:191], v[164:167], v[116:119]
	v_mfma_f32_16x16x32_f16 v[100:103], v[188:191], v[168:171], v[100:103]
	v_mfma_f32_16x16x32_f16 v[84:87], v[188:191], v[172:175], v[84:87]
	v_mfma_f32_16x16x32_f16 v[68:71], v[188:191], v[192:195], v[68:71]
	s_waitcnt vmcnt(7)
	ds_write_b128 v254, v[140:143] offset:3072
	global_load_dwordx4 v[140:143], v250, s[30:31] offset:256
	ds_read_b128 v[164:167], v239
	ds_read_b128 v[168:171], v239 offset:256
	ds_read_b128 v[172:175], v239 offset:512
	ds_read_b128 v[192:195], v239 offset:768
	s_waitcnt lgkmcnt(11)
	v_mfma_f32_16x16x32_f16 v[64:67], v[176:179], v[196:199], v[64:67]
	s_waitcnt lgkmcnt(10)
	v_mfma_f32_16x16x32_f16 v[48:51], v[176:179], v[200:203], v[48:51]
	s_waitcnt lgkmcnt(9)
	v_mfma_f32_16x16x32_f16 v[30:33], v[176:179], v[204:207], v[30:33]
	s_waitcnt lgkmcnt(8)
	v_mfma_f32_16x16x32_f16 v[14:17], v[176:179], v[208:211], v[14:17]
	ds_read_b128 v[176:179], v237
	s_waitcnt vmcnt(7)
	ds_write_b128 v255, v[144:147]
	global_load_dwordx4 v[144:147], v247, s[38:39] offset:256
	v_mfma_f32_16x16x32_f16 v[60:63], v[180:183], v[196:199], v[60:63]
	v_mfma_f32_16x16x32_f16 v[44:47], v[180:183], v[200:203], v[44:47]
	v_mfma_f32_16x16x32_f16 v[26:29], v[180:183], v[204:207], v[26:29]
	v_mfma_f32_16x16x32_f16 v[10:13], v[180:183], v[208:211], v[10:13]
	ds_read_b128 v[180:183], v237 offset:256
	s_waitcnt vmcnt(7)
	ds_write_b128 v255, v[152:155] offset:1024
	global_load_dwordx4 v[152:155], v251, s[38:39] offset:256
	v_mfma_f32_16x16x32_f16 v[56:59], v[184:187], v[196:199], v[56:59]
	v_mfma_f32_16x16x32_f16 v[40:43], v[184:187], v[200:203], v[40:43]
	v_mfma_f32_16x16x32_f16 v[22:25], v[184:187], v[204:207], v[22:25]
	v_mfma_f32_16x16x32_f16 v[6:9], v[184:187], v[208:211], v[6:9]
	ds_read_b128 v[184:187], v237 offset:512
	s_waitcnt vmcnt(7)
	ds_write_b128 v255, v[156:159] offset:2048
	global_load_dwordx4 v[156:159], v252, s[38:39] offset:256
	v_mfma_f32_16x16x32_f16 v[52:55], v[188:191], v[196:199], v[52:55]
	v_mfma_f32_16x16x32_f16 v[36:39], v[188:191], v[200:203], v[36:39]
	v_mfma_f32_16x16x32_f16 v[18:21], v[188:191], v[204:207], v[18:21]
	v_mfma_f32_16x16x32_f16 v[2:5], v[188:191], v[208:211], v[2:5]
	ds_read_b128 v[188:191], v237 offset:768
	s_waitcnt vmcnt(7)
	ds_write_b128 v255, v[160:163] offset:3072
	global_load_dwordx4 v[160:163], v253, s[38:39] offset:256
	ds_read_b128 v[196:199], v239 offset:1024
	ds_read_b128 v[200:203], v239 offset:1280
	ds_read_b128 v[204:207], v239 offset:1536
	ds_read_b128 v[208:211], v239 offset:1792
	s_waitcnt lgkmcnt(11)
	v_mfma_f32_16x16x32_f16 v[148:151], v[176:179], v[164:167], v[148:151]
	v_mfma_f32_16x16x32_f16 v[112:115], v[176:179], v[168:171], v[112:115]
	v_mfma_f32_16x16x32_f16 v[96:99], v[176:179], v[172:175], v[96:99]
	v_mfma_f32_16x16x32_f16 v[80:83], v[176:179], v[192:195], v[80:83]
	s_waitcnt lgkmcnt(9)
	v_mfma_f32_16x16x32_f16 v[128:131], v[180:183], v[164:167], v[128:131]
	v_mfma_f32_16x16x32_f16 v[108:111], v[180:183], v[168:171], v[108:111]
	v_mfma_f32_16x16x32_f16 v[92:95], v[180:183], v[172:175], v[92:95]
	v_mfma_f32_16x16x32_f16 v[76:79], v[180:183], v[192:195], v[76:79]
	s_waitcnt lgkmcnt(7)
	v_mfma_f32_16x16x32_f16 v[120:123], v[184:187], v[164:167], v[120:123]
	v_mfma_f32_16x16x32_f16 v[104:107], v[184:187], v[168:171], v[104:107]
	v_mfma_f32_16x16x32_f16 v[88:91], v[184:187], v[172:175], v[88:91]
	v_mfma_f32_16x16x32_f16 v[72:75], v[184:187], v[192:195], v[72:75]
	s_waitcnt lgkmcnt(5)
	v_mfma_f32_16x16x32_f16 v[116:119], v[188:191], v[164:167], v[116:119]
	v_mfma_f32_16x16x32_f16 v[100:103], v[188:191], v[168:171], v[100:103]
	v_mfma_f32_16x16x32_f16 v[84:87], v[188:191], v[172:175], v[84:87]
	v_mfma_f32_16x16x32_f16 v[68:71], v[188:191], v[192:195], v[68:71]
	s_waitcnt lgkmcnt(0)
	s_barrier
	ds_read_b128 v[164:167], v238
	ds_read_b128 v[168:171], v238 offset:256
	ds_read_b128 v[172:175], v238 offset:512
	ds_read_b128 v[192:195], v238 offset:768
	v_mfma_f32_16x16x32_f16 v[64:67], v[176:179], v[196:199], v[64:67]
	v_mfma_f32_16x16x32_f16 v[48:51], v[176:179], v[200:203], v[48:51]
	v_mfma_f32_16x16x32_f16 v[30:33], v[176:179], v[204:207], v[30:33]
	v_mfma_f32_16x16x32_f16 v[14:17], v[176:179], v[208:211], v[14:17]
	ds_read_b128 v[176:179], v236
	v_mfma_f32_16x16x32_f16 v[60:63], v[180:183], v[196:199], v[60:63]
	v_mfma_f32_16x16x32_f16 v[44:47], v[180:183], v[200:203], v[44:47]
	v_mfma_f32_16x16x32_f16 v[26:29], v[180:183], v[204:207], v[26:29]
	v_mfma_f32_16x16x32_f16 v[10:13], v[180:183], v[208:211], v[10:13]
	ds_read_b128 v[180:183], v236 offset:256
	v_mfma_f32_16x16x32_f16 v[56:59], v[184:187], v[196:199], v[56:59]
	v_mfma_f32_16x16x32_f16 v[40:43], v[184:187], v[200:203], v[40:43]
	v_mfma_f32_16x16x32_f16 v[22:25], v[184:187], v[204:207], v[22:25]
	v_mfma_f32_16x16x32_f16 v[6:9], v[184:187], v[208:211], v[6:9]
	ds_read_b128 v[184:187], v236 offset:512
	v_mfma_f32_16x16x32_f16 v[52:55], v[188:191], v[196:199], v[52:55]
	v_mfma_f32_16x16x32_f16 v[36:39], v[188:191], v[200:203], v[36:39]
	v_mfma_f32_16x16x32_f16 v[18:21], v[188:191], v[204:207], v[18:21]
	v_mfma_f32_16x16x32_f16 v[2:5], v[188:191], v[208:211], v[2:5]
	ds_read_b128 v[188:191], v236 offset:768
	ds_read_b128 v[196:199], v238 offset:1024
	ds_read_b128 v[200:203], v238 offset:1280
	ds_read_b128 v[204:207], v238 offset:1536
	ds_read_b128 v[208:211], v238 offset:1792
	v_xor_b32_e32 v239, 0x8000, v239
	v_xor_b32_e32 v237, 0x8000, v237
	v_xor_b32_e32 v254, 0x8000, v254
	v_xor_b32_e32 v255, 0x8000, v255
	v_xor_b32_e32 v236, 0x8000, v236
	v_xor_b32_e32 v238, 0x8000, v238
	s_addk_i32 s47, 0x800
	s_add_u32 s30, s30, 0x80
	s_addc_u32 s31, s31, 0
	s_add_u32 s38, s38, 0x80
	s_addc_u32 s39, s39, 0
	s_mov_b32 s48, s49
	s_branch .Lg3_loop
.Lg3_warm:
	s_waitcnt lgkmcnt(7)
	v_mfma_f32_16x16x32_f16 v[148:151], v[176:179], v[164:167], v[148:151]
	v_mfma_f32_16x16x32_f16 v[112:115], v[176:179], v[168:171], v[112:115]
	v_mfma_f32_16x16x32_f16 v[96:99], v[176:179], v[172:175], v[96:99]
	v_mfma_f32_16x16x32_f16 v[80:83], v[176:179], v[192:195], v[80:83]
	s_waitcnt vmcnt(7)
	ds_write_b128 v254, v[124:127]
	s_waitcnt lgkmcnt(7)
	v_mfma_f32_16x16x32_f16 v[128:131], v[180:183], v[164:167], v[128:131]
	v_mfma_f32_16x16x32_f16 v[108:111], v[180:183], v[168:171], v[108:111]
	v_mfma_f32_16x16x32_f16 v[92:95], v[180:183], v[172:175], v[92:95]
	v_mfma_f32_16x16x32_f16 v[76:79], v[180:183], v[192:195], v[76:79]
	s_waitcnt vmcnt(6)
	ds_write_b128 v254, v[132:135] offset:1024
	s_waitcnt lgkmcnt(7)
	v_mfma_f32_16x16x32_f16 v[120:123], v[184:187], v[164:167], v[120:123]
	v_mfma_f32_16x16x32_f16 v[104:107], v[184:187], v[168:171], v[104:107]
	v_mfma_f32_16x16x32_f16 v[88:91], v[184:187], v[172:175], v[88:91]
	v_mfma_f32_16x16x32_f16 v[72:75], v[184:187], v[192:195], v[72:75]
	s_waitcnt vmcnt(5)
	ds_write_b128 v254, v[136:139] offset:2048
	s_waitcnt lgkmcnt(7)
	v_mfma_f32_16x16x32_f16 v[116:119], v[188:191], v[164:167], v[116:119]
	v_mfma_f32_16x16x32_f16 v[100:103], v[188:191], v[168:171], v[100:103]
	v_mfma_f32_16x16x32_f16 v[84:87], v[188:191], v[172:175], v[84:87]
	v_mfma_f32_16x16x32_f16 v[68:71], v[188:191], v[192:195], v[68:71]
	s_waitcnt vmcnt(4)
	ds_write_b128 v254, v[140:143] offset:3072
	ds_read_b128 v[164:167], v239
	ds_read_b128 v[168:171], v239 offset:256
	ds_read_b128 v[172:175], v239 offset:512
	ds_read_b128 v[192:195], v239 offset:768
	s_waitcnt lgkmcnt(11)
	v_mfma_f32_16x16x32_f16 v[64:67], v[176:179], v[196:199], v[64:67]
	s_waitcnt lgkmcnt(10)
	v_mfma_f32_16x16x32_f16 v[48:51], v[176:179], v[200:203], v[48:51]
	s_waitcnt lgkmcnt(9)
	v_mfma_f32_16x16x32_f16 v[30:33], v[176:179], v[204:207], v[30:33]
	s_waitcnt lgkmcnt(8)
	v_mfma_f32_16x16x32_f16 v[14:17], v[176:179], v[208:211], v[14:17]
	ds_read_b128 v[176:179], v237
	s_waitcnt vmcnt(3)
	ds_write_b128 v255, v[144:147]
	v_mfma_f32_16x16x32_f16 v[60:63], v[180:183], v[196:199], v[60:63]
	v_mfma_f32_16x16x32_f16 v[44:47], v[180:183], v[200:203], v[44:47]
	v_mfma_f32_16x16x32_f16 v[26:29], v[180:183], v[204:207], v[26:29]
	v_mfma_f32_16x16x32_f16 v[10:13], v[180:183], v[208:211], v[10:13]
	ds_read_b128 v[180:183], v237 offset:256
	s_waitcnt vmcnt(2)
	ds_write_b128 v255, v[152:155] offset:1024
	v_mfma_f32_16x16x32_f16 v[56:59], v[184:187], v[196:199], v[56:59]
	v_mfma_f32_16x16x32_f16 v[40:43], v[184:187], v[200:203], v[40:43]
	v_mfma_f32_16x16x32_f16 v[22:25], v[184:187], v[204:207], v[22:25]
	v_mfma_f32_16x16x32_f16 v[6:9], v[184:187], v[208:211], v[6:9]
	ds_read_b128 v[184:187], v237 offset:512
	s_waitcnt vmcnt(1)
	ds_write_b128 v255, v[156:159] offset:2048
	v_mfma_f32_16x16x32_f16 v[52:55], v[188:191], v[196:199], v[52:55]
	v_mfma_f32_16x16x32_f16 v[36:39], v[188:191], v[200:203], v[36:39]
	v_mfma_f32_16x16x32_f16 v[18:21], v[188:191], v[204:207], v[18:21]
	v_mfma_f32_16x16x32_f16 v[2:5], v[188:191], v[208:211], v[2:5]
	ds_read_b128 v[188:191], v237 offset:768
	s_waitcnt vmcnt(0)
	ds_write_b128 v255, v[160:163] offset:3072
	ds_read_b128 v[196:199], v239 offset:1024
	ds_read_b128 v[200:203], v239 offset:1280
	ds_read_b128 v[204:207], v239 offset:1536
	ds_read_b128 v[208:211], v239 offset:1792
	s_waitcnt lgkmcnt(11)
	v_mfma_f32_16x16x32_f16 v[148:151], v[176:179], v[164:167], v[148:151]
	v_mfma_f32_16x16x32_f16 v[112:115], v[176:179], v[168:171], v[112:115]
	v_mfma_f32_16x16x32_f16 v[96:99], v[176:179], v[172:175], v[96:99]
	v_mfma_f32_16x16x32_f16 v[80:83], v[176:179], v[192:195], v[80:83]
	s_waitcnt lgkmcnt(9)
	v_mfma_f32_16x16x32_f16 v[128:131], v[180:183], v[164:167], v[128:131]
	v_mfma_f32_16x16x32_f16 v[108:111], v[180:183], v[168:171], v[108:111]
	v_mfma_f32_16x16x32_f16 v[92:95], v[180:183], v[172:175], v[92:95]
	v_mfma_f32_16x16x32_f16 v[76:79], v[180:183], v[192:195], v[76:79]
	s_waitcnt lgkmcnt(7)
	v_mfma_f32_16x16x32_f16 v[120:123], v[184:187], v[164:167], v[120:123]
	v_mfma_f32_16x16x32_f16 v[104:107], v[184:187], v[168:171], v[104:107]
	v_mfma_f32_16x16x32_f16 v[88:91], v[184:187], v[172:175], v[88:91]
	v_mfma_f32_16x16x32_f16 v[72:75], v[184:187], v[192:195], v[72:75]
	s_waitcnt lgkmcnt(5)
	v_mfma_f32_16x16x32_f16 v[116:119], v[188:191], v[164:167], v[116:119]
	v_mfma_f32_16x16x32_f16 v[100:103], v[188:191], v[168:171], v[100:103]
	v_mfma_f32_16x16x32_f16 v[84:87], v[188:191], v[172:175], v[84:87]
	v_mfma_f32_16x16x32_f16 v[68:71], v[188:191], v[192:195], v[68:71]
	s_waitcnt lgkmcnt(0)
	s_barrier
	ds_read_b128 v[164:167], v238
	ds_read_b128 v[168:171], v238 offset:256
	ds_read_b128 v[172:175], v238 offset:512
	ds_read_b128 v[192:195], v238 offset:768
	v_mfma_f32_16x16x32_f16 v[64:67], v[176:179], v[196:199], v[64:67]
	v_mfma_f32_16x16x32_f16 v[48:51], v[176:179], v[200:203], v[48:51]
	v_mfma_f32_16x16x32_f16 v[30:33], v[176:179], v[204:207], v[30:33]
	v_mfma_f32_16x16x32_f16 v[14:17], v[176:179], v[208:211], v[14:17]
	ds_read_b128 v[176:179], v236
	v_mfma_f32_16x16x32_f16 v[60:63], v[180:183], v[196:199], v[60:63]
	v_mfma_f32_16x16x32_f16 v[44:47], v[180:183], v[200:203], v[44:47]
	v_mfma_f32_16x16x32_f16 v[26:29], v[180:183], v[204:207], v[26:29]
	v_mfma_f32_16x16x32_f16 v[10:13], v[180:183], v[208:211], v[10:13]
	ds_read_b128 v[180:183], v236 offset:256
	v_mfma_f32_16x16x32_f16 v[56:59], v[184:187], v[196:199], v[56:59]
	v_mfma_f32_16x16x32_f16 v[40:43], v[184:187], v[200:203], v[40:43]
	v_mfma_f32_16x16x32_f16 v[22:25], v[184:187], v[204:207], v[22:25]
	v_mfma_f32_16x16x32_f16 v[6:9], v[184:187], v[208:211], v[6:9]
	ds_read_b128 v[184:187], v236 offset:512
	v_mfma_f32_16x16x32_f16 v[52:55], v[188:191], v[196:199], v[52:55]
	v_mfma_f32_16x16x32_f16 v[36:39], v[188:191], v[200:203], v[36:39]
	v_mfma_f32_16x16x32_f16 v[18:21], v[188:191], v[204:207], v[18:21]
	v_mfma_f32_16x16x32_f16 v[2:5], v[188:191], v[208:211], v[2:5]
	ds_read_b128 v[188:191], v236 offset:768
	ds_read_b128 v[196:199], v238 offset:1024
	ds_read_b128 v[200:203], v238 offset:1280
	ds_read_b128 v[204:207], v238 offset:1536
	ds_read_b128 v[208:211], v238 offset:1792
	v_xor_b32_e32 v239, 0x8000, v239
	v_xor_b32_e32 v237, 0x8000, v237
	v_xor_b32_e32 v254, 0x8000, v254
	v_xor_b32_e32 v255, 0x8000, v255
	v_xor_b32_e32 v236, 0x8000, v236
	v_xor_b32_e32 v238, 0x8000, v238
	s_addk_i32 s47, 0x800
	s_mov_b32 s48, s49
	s_branch .Lg3_loop

.Lg4_loop:
	s_add_i32 s39, s38, 1
	s_cmp_ge_i32 s39, s3
	s_cbranch_scc1 .Lg4_cold
	s_add_i32 s38, s38, 2
	s_cmp_ge_i32 s38, s3
	s_cbranch_scc1 .Lg4_warm
	s_waitcnt lgkmcnt(7)
	v_mfma_f32_16x16x32_f16 v[156:159], v[176:179], v[164:167], v[156:159]
	v_mfma_f32_16x16x32_f16 v[128:131], v[176:179], v[168:171], v[128:131]
	v_mfma_f32_16x16x32_f16 v[96:99], v[176:179], v[172:175], v[96:99]
	v_mfma_f32_16x16x32_f16 v[80:83], v[176:179], v[192:195], v[80:83]
	s_waitcnt vmcnt(7)
	ds_write_b128 v254, v[100:103]
	global_load_dwordx4 v[100:103], v246, s[28:29] offset:256
	s_waitcnt lgkmcnt(7)
	v_mfma_f32_16x16x32_f16 v[152:155], v[180:183], v[164:167], v[152:155]
	v_mfma_f32_16x16x32_f16 v[120:123], v[180:183], v[168:171], v[120:123]
	v_mfma_f32_16x16x32_f16 v[92:95], v[180:183], v[172:175], v[92:95]
	v_mfma_f32_16x16x32_f16 v[76:79], v[180:183], v[192:195], v[76:79]
	s_waitcnt vmcnt(7)
	ds_write_b128 v254, v[108:111] offset:1024
	global_load_dwordx4 v[108:111], v248, s[28:29] offset:256
	s_waitcnt lgkmcnt(7)
	v_mfma_f32_16x16x32_f16 v[140:143], v[184:187], v[164:167], v[140:143]
	v_mfma_f32_16x16x32_f16 v[112:115], v[184:187], v[168:171], v[112:115]
	v_mfma_f32_16x16x32_f16 v[88:91], v[184:187], v[172:175], v[88:91]
	v_mfma_f32_16x16x32_f16 v[72:75], v[184:187], v[192:195], v[72:75]
	s_waitcnt vmcnt(7)
	ds_write_b128 v254, v[116:119] offset:2048
	global_load_dwordx4 v[116:119], v249, s[28:29] offset:256
	s_waitcnt lgkmcnt(7)
	v_mfma_f32_16x16x32_f16 v[136:139], v[188:191], v[164:167], v[136:139]
	v_mfma_f32_16x16x32_f16 v[104:107], v[188:191], v[168:171], v[104:107]
	v_mfma_f32_16x16x32_f16 v[84:87], v[188:191], v[172:175], v[84:87]
	v_mfma_f32_16x16x32_f16 v[68:71], v[188:191], v[192:195], v[68:71]
	s_waitcnt vmcnt(7)
	ds_write_b128 v254, v[124:127] offset:3072
	global_load_dwordx4 v[124:127], v250, s[28:29] offset:256
	ds_read_b128 v[164:167], v239
	ds_read_b128 v[168:171], v239 offset:256
	ds_read_b128 v[172:175], v239 offset:512
	ds_read_b128 v[192:195], v239 offset:768
	s_waitcnt lgkmcnt(11)
	v_mfma_f32_16x16x32_f16 v[64:67], v[176:179], v[196:199], v[64:67]
	s_waitcnt lgkmcnt(10)
	v_mfma_f32_16x16x32_f16 v[48:51], v[176:179], v[200:203], v[48:51]
	s_waitcnt lgkmcnt(9)
	v_mfma_f32_16x16x32_f16 v[30:33], v[176:179], v[204:207], v[30:33]
	s_waitcnt lgkmcnt(8)
	v_mfma_f32_16x16x32_f16 v[14:17], v[176:179], v[208:211], v[14:17]
	ds_read_b128 v[176:179], v237
	s_waitcnt vmcnt(7)
	ds_write_b128 v255, v[132:135]
	global_load_dwordx4 v[132:135], v247, s[30:31] offset:256
	v_mfma_f32_16x16x32_f16 v[60:63], v[180:183], v[196:199], v[60:63]
	v_mfma_f32_16x16x32_f16 v[44:47], v[180:183], v[200:203], v[44:47]
	v_mfma_f32_16x16x32_f16 v[26:29], v[180:183], v[204:207], v[26:29]
	v_mfma_f32_16x16x32_f16 v[10:13], v[180:183], v[208:211], v[10:13]
	ds_read_b128 v[180:183], v237 offset:256
	s_waitcnt vmcnt(7)
	ds_write_b128 v255, v[144:147] offset:1024
	global_load_dwordx4 v[144:147], v251, s[30:31] offset:256
	v_mfma_f32_16x16x32_f16 v[56:59], v[184:187], v[196:199], v[56:59]
	v_mfma_f32_16x16x32_f16 v[40:43], v[184:187], v[200:203], v[40:43]
	v_mfma_f32_16x16x32_f16 v[22:25], v[184:187], v[204:207], v[22:25]
	v_mfma_f32_16x16x32_f16 v[6:9], v[184:187], v[208:211], v[6:9]
	ds_read_b128 v[184:187], v237 offset:512
	s_waitcnt vmcnt(7)
	ds_write_b128 v255, v[148:151] offset:2048
	global_load_dwordx4 v[148:151], v252, s[30:31] offset:256
	v_mfma_f32_16x16x32_f16 v[52:55], v[188:191], v[196:199], v[52:55]
	v_mfma_f32_16x16x32_f16 v[36:39], v[188:191], v[200:203], v[36:39]
	v_mfma_f32_16x16x32_f16 v[18:21], v[188:191], v[204:207], v[18:21]
	v_mfma_f32_16x16x32_f16 v[2:5], v[188:191], v[208:211], v[2:5]
	ds_read_b128 v[188:191], v237 offset:768
	s_waitcnt vmcnt(7)
	ds_write_b128 v255, v[160:163] offset:3072
	global_load_dwordx4 v[160:163], v253, s[30:31] offset:256
	ds_read_b128 v[196:199], v239 offset:1024
	ds_read_b128 v[200:203], v239 offset:1280
	ds_read_b128 v[204:207], v239 offset:1536
	ds_read_b128 v[208:211], v239 offset:1792
	s_waitcnt lgkmcnt(11)
	v_mfma_f32_16x16x32_f16 v[156:159], v[176:179], v[164:167], v[156:159]
	v_mfma_f32_16x16x32_f16 v[128:131], v[176:179], v[168:171], v[128:131]
	v_mfma_f32_16x16x32_f16 v[96:99], v[176:179], v[172:175], v[96:99]
	v_mfma_f32_16x16x32_f16 v[80:83], v[176:179], v[192:195], v[80:83]
	s_waitcnt lgkmcnt(9)
	v_mfma_f32_16x16x32_f16 v[152:155], v[180:183], v[164:167], v[152:155]
	v_mfma_f32_16x16x32_f16 v[120:123], v[180:183], v[168:171], v[120:123]
	v_mfma_f32_16x16x32_f16 v[92:95], v[180:183], v[172:175], v[92:95]
	v_mfma_f32_16x16x32_f16 v[76:79], v[180:183], v[192:195], v[76:79]
	s_waitcnt lgkmcnt(7)
	v_mfma_f32_16x16x32_f16 v[140:143], v[184:187], v[164:167], v[140:143]
	v_mfma_f32_16x16x32_f16 v[112:115], v[184:187], v[168:171], v[112:115]
	v_mfma_f32_16x16x32_f16 v[88:91], v[184:187], v[172:175], v[88:91]
	v_mfma_f32_16x16x32_f16 v[72:75], v[184:187], v[192:195], v[72:75]
	s_waitcnt lgkmcnt(5)
	v_mfma_f32_16x16x32_f16 v[136:139], v[188:191], v[164:167], v[136:139]
	v_mfma_f32_16x16x32_f16 v[104:107], v[188:191], v[168:171], v[104:107]
	v_mfma_f32_16x16x32_f16 v[84:87], v[188:191], v[172:175], v[84:87]
	v_mfma_f32_16x16x32_f16 v[68:71], v[188:191], v[192:195], v[68:71]
	s_waitcnt lgkmcnt(0)
	s_barrier
	ds_read_b128 v[164:167], v238
	ds_read_b128 v[168:171], v238 offset:256
	ds_read_b128 v[172:175], v238 offset:512
	ds_read_b128 v[192:195], v238 offset:768
	v_mfma_f32_16x16x32_f16 v[64:67], v[176:179], v[196:199], v[64:67]
	v_mfma_f32_16x16x32_f16 v[48:51], v[176:179], v[200:203], v[48:51]
	v_mfma_f32_16x16x32_f16 v[30:33], v[176:179], v[204:207], v[30:33]
	v_mfma_f32_16x16x32_f16 v[14:17], v[176:179], v[208:211], v[14:17]
	ds_read_b128 v[176:179], v236
	v_mfma_f32_16x16x32_f16 v[60:63], v[180:183], v[196:199], v[60:63]
	v_mfma_f32_16x16x32_f16 v[44:47], v[180:183], v[200:203], v[44:47]
	v_mfma_f32_16x16x32_f16 v[26:29], v[180:183], v[204:207], v[26:29]
	v_mfma_f32_16x16x32_f16 v[10:13], v[180:183], v[208:211], v[10:13]
	ds_read_b128 v[180:183], v236 offset:256
	v_mfma_f32_16x16x32_f16 v[56:59], v[184:187], v[196:199], v[56:59]
	v_mfma_f32_16x16x32_f16 v[40:43], v[184:187], v[200:203], v[40:43]
	v_mfma_f32_16x16x32_f16 v[22:25], v[184:187], v[204:207], v[22:25]
	v_mfma_f32_16x16x32_f16 v[6:9], v[184:187], v[208:211], v[6:9]
	ds_read_b128 v[184:187], v236 offset:512
	v_mfma_f32_16x16x32_f16 v[52:55], v[188:191], v[196:199], v[52:55]
	v_mfma_f32_16x16x32_f16 v[36:39], v[188:191], v[200:203], v[36:39]
	v_mfma_f32_16x16x32_f16 v[18:21], v[188:191], v[204:207], v[18:21]
	v_mfma_f32_16x16x32_f16 v[2:5], v[188:191], v[208:211], v[2:5]
	ds_read_b128 v[188:191], v236 offset:768
	ds_read_b128 v[196:199], v238 offset:1024
	ds_read_b128 v[200:203], v238 offset:1280
	ds_read_b128 v[204:207], v238 offset:1536
	ds_read_b128 v[208:211], v238 offset:1792
	v_xor_b32_e32 v239, 0x8000, v239
	v_xor_b32_e32 v237, 0x8000, v237
	v_xor_b32_e32 v254, 0x8000, v254
	v_xor_b32_e32 v255, 0x8000, v255
	v_xor_b32_e32 v236, 0x8000, v236
	v_xor_b32_e32 v238, 0x8000, v238
	s_addk_i32 s23, 0x800
	s_add_u32 s28, s28, 0x80
	s_addc_u32 s29, s29, 0
	s_add_u32 s30, s30, 0x80
	s_addc_u32 s31, s31, 0
	s_mov_b32 s38, s39
	s_branch .Lg4_loop
.Lg4_warm:
	s_waitcnt lgkmcnt(7)
	v_mfma_f32_16x16x32_f16 v[156:159], v[176:179], v[164:167], v[156:159]
	v_mfma_f32_16x16x32_f16 v[128:131], v[176:179], v[168:171], v[128:131]
	v_mfma_f32_16x16x32_f16 v[96:99], v[176:179], v[172:175], v[96:99]
	v_mfma_f32_16x16x32_f16 v[80:83], v[176:179], v[192:195], v[80:83]
	s_waitcnt vmcnt(7)
	ds_write_b128 v254, v[100:103]
	s_waitcnt lgkmcnt(7)
	v_mfma_f32_16x16x32_f16 v[152:155], v[180:183], v[164:167], v[152:155]
	v_mfma_f32_16x16x32_f16 v[120:123], v[180:183], v[168:171], v[120:123]
	v_mfma_f32_16x16x32_f16 v[92:95], v[180:183], v[172:175], v[92:95]
	v_mfma_f32_16x16x32_f16 v[76:79], v[180:183], v[192:195], v[76:79]
	s_waitcnt vmcnt(6)
	ds_write_b128 v254, v[108:111] offset:1024
	s_waitcnt lgkmcnt(7)
	v_mfma_f32_16x16x32_f16 v[140:143], v[184:187], v[164:167], v[140:143]
	v_mfma_f32_16x16x32_f16 v[112:115], v[184:187], v[168:171], v[112:115]
	v_mfma_f32_16x16x32_f16 v[88:91], v[184:187], v[172:175], v[88:91]
	v_mfma_f32_16x16x32_f16 v[72:75], v[184:187], v[192:195], v[72:75]
	s_waitcnt vmcnt(5)
	ds_write_b128 v254, v[116:119] offset:2048
	s_waitcnt lgkmcnt(7)
	v_mfma_f32_16x16x32_f16 v[136:139], v[188:191], v[164:167], v[136:139]
	v_mfma_f32_16x16x32_f16 v[104:107], v[188:191], v[168:171], v[104:107]
	v_mfma_f32_16x16x32_f16 v[84:87], v[188:191], v[172:175], v[84:87]
	v_mfma_f32_16x16x32_f16 v[68:71], v[188:191], v[192:195], v[68:71]
	s_waitcnt vmcnt(4)
	ds_write_b128 v254, v[124:127] offset:3072
	ds_read_b128 v[164:167], v239
	ds_read_b128 v[168:171], v239 offset:256
	ds_read_b128 v[172:175], v239 offset:512
	ds_read_b128 v[192:195], v239 offset:768
	s_waitcnt lgkmcnt(11)
	v_mfma_f32_16x16x32_f16 v[64:67], v[176:179], v[196:199], v[64:67]
	s_waitcnt lgkmcnt(10)
	v_mfma_f32_16x16x32_f16 v[48:51], v[176:179], v[200:203], v[48:51]
	s_waitcnt lgkmcnt(9)
	v_mfma_f32_16x16x32_f16 v[30:33], v[176:179], v[204:207], v[30:33]
	s_waitcnt lgkmcnt(8)
	v_mfma_f32_16x16x32_f16 v[14:17], v[176:179], v[208:211], v[14:17]
	ds_read_b128 v[176:179], v237
	s_waitcnt vmcnt(3)
	ds_write_b128 v255, v[132:135]
	v_mfma_f32_16x16x32_f16 v[60:63], v[180:183], v[196:199], v[60:63]
	v_mfma_f32_16x16x32_f16 v[44:47], v[180:183], v[200:203], v[44:47]
	v_mfma_f32_16x16x32_f16 v[26:29], v[180:183], v[204:207], v[26:29]
	v_mfma_f32_16x16x32_f16 v[10:13], v[180:183], v[208:211], v[10:13]
	ds_read_b128 v[180:183], v237 offset:256
	s_waitcnt vmcnt(2)
	ds_write_b128 v255, v[144:147] offset:1024
	v_mfma_f32_16x16x32_f16 v[56:59], v[184:187], v[196:199], v[56:59]
	v_mfma_f32_16x16x32_f16 v[40:43], v[184:187], v[200:203], v[40:43]
	v_mfma_f32_16x16x32_f16 v[22:25], v[184:187], v[204:207], v[22:25]
	v_mfma_f32_16x16x32_f16 v[6:9], v[184:187], v[208:211], v[6:9]
	ds_read_b128 v[184:187], v237 offset:512
	s_waitcnt vmcnt(1)
	ds_write_b128 v255, v[148:151] offset:2048
	v_mfma_f32_16x16x32_f16 v[52:55], v[188:191], v[196:199], v[52:55]
	v_mfma_f32_16x16x32_f16 v[36:39], v[188:191], v[200:203], v[36:39]
	v_mfma_f32_16x16x32_f16 v[18:21], v[188:191], v[204:207], v[18:21]
	v_mfma_f32_16x16x32_f16 v[2:5], v[188:191], v[208:211], v[2:5]
	ds_read_b128 v[188:191], v237 offset:768
	s_waitcnt vmcnt(0)
	ds_write_b128 v255, v[160:163] offset:3072
	ds_read_b128 v[196:199], v239 offset:1024
	ds_read_b128 v[200:203], v239 offset:1280
	ds_read_b128 v[204:207], v239 offset:1536
	ds_read_b128 v[208:211], v239 offset:1792
	s_waitcnt lgkmcnt(11)
	v_mfma_f32_16x16x32_f16 v[156:159], v[176:179], v[164:167], v[156:159]
	v_mfma_f32_16x16x32_f16 v[128:131], v[176:179], v[168:171], v[128:131]
	v_mfma_f32_16x16x32_f16 v[96:99], v[176:179], v[172:175], v[96:99]
	v_mfma_f32_16x16x32_f16 v[80:83], v[176:179], v[192:195], v[80:83]
	s_waitcnt lgkmcnt(9)
	v_mfma_f32_16x16x32_f16 v[152:155], v[180:183], v[164:167], v[152:155]
	v_mfma_f32_16x16x32_f16 v[120:123], v[180:183], v[168:171], v[120:123]
	v_mfma_f32_16x16x32_f16 v[92:95], v[180:183], v[172:175], v[92:95]
	v_mfma_f32_16x16x32_f16 v[76:79], v[180:183], v[192:195], v[76:79]
	s_waitcnt lgkmcnt(7)
	v_mfma_f32_16x16x32_f16 v[140:143], v[184:187], v[164:167], v[140:143]
	v_mfma_f32_16x16x32_f16 v[112:115], v[184:187], v[168:171], v[112:115]
	v_mfma_f32_16x16x32_f16 v[88:91], v[184:187], v[172:175], v[88:91]
	v_mfma_f32_16x16x32_f16 v[72:75], v[184:187], v[192:195], v[72:75]
	s_waitcnt lgkmcnt(5)
	v_mfma_f32_16x16x32_f16 v[136:139], v[188:191], v[164:167], v[136:139]
	v_mfma_f32_16x16x32_f16 v[104:107], v[188:191], v[168:171], v[104:107]
	v_mfma_f32_16x16x32_f16 v[84:87], v[188:191], v[172:175], v[84:87]
	v_mfma_f32_16x16x32_f16 v[68:71], v[188:191], v[192:195], v[68:71]
	s_waitcnt lgkmcnt(0)
	s_barrier
	ds_read_b128 v[164:167], v238
	ds_read_b128 v[168:171], v238 offset:256
	ds_read_b128 v[172:175], v238 offset:512
	ds_read_b128 v[192:195], v238 offset:768
	v_mfma_f32_16x16x32_f16 v[64:67], v[176:179], v[196:199], v[64:67]
	v_mfma_f32_16x16x32_f16 v[48:51], v[176:179], v[200:203], v[48:51]
	v_mfma_f32_16x16x32_f16 v[30:33], v[176:179], v[204:207], v[30:33]
	v_mfma_f32_16x16x32_f16 v[14:17], v[176:179], v[208:211], v[14:17]
	ds_read_b128 v[176:179], v236
	v_mfma_f32_16x16x32_f16 v[60:63], v[180:183], v[196:199], v[60:63]
	v_mfma_f32_16x16x32_f16 v[44:47], v[180:183], v[200:203], v[44:47]
	v_mfma_f32_16x16x32_f16 v[26:29], v[180:183], v[204:207], v[26:29]
	v_mfma_f32_16x16x32_f16 v[10:13], v[180:183], v[208:211], v[10:13]
	ds_read_b128 v[180:183], v236 offset:256
	v_mfma_f32_16x16x32_f16 v[56:59], v[184:187], v[196:199], v[56:59]
	v_mfma_f32_16x16x32_f16 v[40:43], v[184:187], v[200:203], v[40:43]
	v_mfma_f32_16x16x32_f16 v[22:25], v[184:187], v[204:207], v[22:25]
	v_mfma_f32_16x16x32_f16 v[6:9], v[184:187], v[208:211], v[6:9]
	ds_read_b128 v[184:187], v236 offset:512
	v_mfma_f32_16x16x32_f16 v[52:55], v[188:191], v[196:199], v[52:55]
	v_mfma_f32_16x16x32_f16 v[36:39], v[188:191], v[200:203], v[36:39]
	v_mfma_f32_16x16x32_f16 v[18:21], v[188:191], v[204:207], v[18:21]
	v_mfma_f32_16x16x32_f16 v[2:5], v[188:191], v[208:211], v[2:5]
	ds_read_b128 v[188:191], v236 offset:768
	ds_read_b128 v[196:199], v238 offset:1024
	ds_read_b128 v[200:203], v238 offset:1280
	ds_read_b128 v[204:207], v238 offset:1536
	ds_read_b128 v[208:211], v238 offset:1792
	v_xor_b32_e32 v239, 0x8000, v239
	v_xor_b32_e32 v237, 0x8000, v237
	v_xor_b32_e32 v254, 0x8000, v254
	v_xor_b32_e32 v255, 0x8000, v255
	v_xor_b32_e32 v236, 0x8000, v236
	v_xor_b32_e32 v238, 0x8000, v238
	s_addk_i32 s23, 0x800
	s_mov_b32 s38, s39
	s_branch .Lg4_loop

.LBB0_812:
	s_waitcnt vmcnt(1)
	s_add_i32 s3, s24, 1
	s_mul_i32 s23, s3, s33
	s_mul_hi_u32 s3, s3, s33
	s_add_u32 s30, s23, s37
	s_addc_u32 s31, s3, 0
	s_lshr_b64 s[28:29], s[30:31], 2
	s_and_b32 s3, s28, -8
	s_or_b32 s23, s3, s35
	s_mov_b32 s98, 0
	s_cmp_gt_i32 s23, 63
	s_cbranch_scc1 .Lnxk0_skip
	s_cmp_eq_u32 s22, 15
	s_cbranch_scc1 .Lnxk0_skip
	s_load_dwordx2 s[100:101], s[0:1], 0xf8
	s_lshr_b32 s3, s23, 1
	s_lshl_b32 s3, s3, 2
	s_and_b32 s28, s30, 3
	s_or_b32 s3, s3, s28
	s_and_b32 s28, s23, 1
	s_lshl_b32 s28, s28, 3
	s_bfe_u32 s29, s30, 0x30002
	s_or_b32 s28, s28, s29
	s_lshl_b32 s3, s3, 19
	s_lshl_b32 s28, s28, 19
	s_add_u32 s98, s16, s3
	s_addc_u32 s99, s17, 0
	s_waitcnt lgkmcnt(0)
	s_add_u32 s100, s100, s28
	s_addc_u32 s101, s101, 0
	s_sub_u32 s98, s98, 0
	s_subb_u32 s99, s99, 0
	s_sub_u32 s100, s100, 0
	s_subb_u32 s101, s101, 0
	v_add_u32_e32 v246, v227, v228
	v_add_u32_e32 v247, v227, v231
	v_lshlrev_b32_e32 v246, 1, v246
	v_lshlrev_b32_e32 v247, 1, v247
	v_add_u32_e32 v248, 0x20000, v246
	v_add_u32_e32 v249, 0x40000, v246
	v_add_u32_e32 v250, 0x60000, v246
	v_add_u32_e32 v251, 0x20000, v247
	v_add_u32_e32 v252, 0x40000, v247
	v_add_u32_e32 v253, 0x60000, v247
	global_load_dwordx4 v[164:167], v246, s[98:99]
	global_load_dwordx4 v[168:171], v248, s[98:99]
	global_load_dwordx4 v[172:175], v249, s[98:99]
	global_load_dwordx4 v[192:195], v250, s[98:99]
	global_load_dwordx4 v[176:179], v247, s[100:101]
	global_load_dwordx4 v[180:183], v251, s[100:101]
	global_load_dwordx4 v[184:187], v252, s[100:101]
	global_load_dwordx4 v[188:191], v253, s[100:101]
	s_mov_b32 s98, 1
